# P1 k-section epilogue: xor-16/xor-32 lane sums via v_permlane16_swap / v_permlane32_swap instead of ds_bpermute round trips with recomputed indices
# speedup vs baseline: 1.0016x; 1.0016x over previous
.Lmy_e1_generic:
	s_xor_b64 s[74:75], s[74:75], -1
	s_mov_b64 s[78:79], -1
	s_xor_b64 s[76:77], s[76:77], -1
	s_and_b64 vcc, exec, s[74:75]
	s_cbranch_vccz .LBB0_197
	s_and_b64 vcc, exec, s[76:77]
	s_cbranch_vccz .LBB0_194
	s_and_b64 vcc, exec, s[56:57]
	s_cbranch_vccz .LBB0_191
	s_andn2_b64 vcc, exec, s[54:55]
	v_mov_b32_e32 v162, 0
	s_cbranch_vccnz .LBB0_190
	v_pk_mul_f32 v[146:147], v[128:129], v[128:129]
	v_pk_mul_f32 v[148:149], v[126:127], v[126:127]
	s_nop 0
	v_pk_mov_b32 v[150:151], v[148:149], v[146:147] op_sel:[1,0]
	v_mov_b32_e32 v149, v147
	v_pk_add_f32 v[146:147], v[150:151], v[148:149]
	v_pk_mul_f32 v[148:149], v[124:125], v[124:125]
	v_pk_mul_f32 v[150:151], v[122:123], v[122:123]
	v_mov_b32_e32 v152, v148
	v_mov_b32_e32 v153, v150
	v_mov_b32_e32 v150, v149
	v_pk_add_f32 v[148:149], v[152:153], v[150:151]
	v_add_f32_e32 v146, v146, v147
	v_add_f32_e32 v146, v146, v149
	v_add_f32_e32 v146, v148, v146
	v_and_b32_e32 v148, 64, v160
	v_add_u32_e32 v148, 64, v148
	v_mov_b32_e32 v147, v146
	s_nop 1
	v_permlane16_swap_b32_e32 v146, v147
	v_add_f32_e32 v146, v146, v147
	v_mov_b32_e32 v147, v146
	s_nop 1
	v_permlane32_swap_b32_e32 v146, v147
	v_add_f32_e32 v146, v146, v147
	v_max_f32_e32 v162, 0, v146

.LBB0_199:
	s_lshl_b32 s6, s6, 8
	s_add_i32 s6, s7, s6
	v_or_b32_e32 v122, s6, v156
	s_lshl_b32 s6, s72, 1
	s_add_u32 s6, s38, s6
	v_lshl_add_u32 v161, s8, 8, v154
	s_addc_u32 s7, s39, 0
	v_ashrrev_i32_e32 v123, 31, v122
	v_lshl_add_u64 v[122:123], v[122:123], 1, s[6:7]
	v_mad_i64_i32 v[124:125], s[6:7], s70, v161, 0
	v_lshl_add_u64 v[124:125], v[124:125], 1, v[122:123]
	v_cvt_pk_bf16_f32 v126, v146, v147
	v_cvt_pk_bf16_f32 v127, v148, v149
	v_cvt_pk_bf16_f32 v128, v150, v151
	v_cvt_pk_bf16_f32 v129, v152, v153
	global_store_dwordx4 v[124:125], v[126:129], off
	s_mov_b64 s[72:73], -1
	s_andn2_b64 vcc, exec, s[74:75]
	v_cndmask_b32_e64 v126, 0, 1, s[74:75]
	v_cmp_ne_u32_e64 s[8:9], 1, v126
	v_cndmask_b32_e64 v126, 0, 1, s[76:77]
	v_cmp_ne_u32_e64 s[6:7], 1, v126
	s_cbranch_vccnz .LBB0_211
	s_and_b64 vcc, exec, s[6:7]
	s_cbranch_vccnz .LBB0_208
	s_andn2_b64 vcc, exec, s[56:57]
	s_cbranch_vccnz .LBB0_205
	s_andn2_b64 vcc, exec, s[54:55]
	v_mov_b32_e32 v150, v162
	s_cbranch_vccnz .LBB0_204
	v_pk_mul_f32 v[126:127], v[120:121], v[120:121]
	v_pk_mul_f32 v[128:129], v[118:119], v[118:119]
	s_nop 0
	v_pk_mov_b32 v[146:147], v[128:129], v[126:127] op_sel:[1,0]
	v_mov_b32_e32 v129, v127
	v_pk_add_f32 v[126:127], v[146:147], v[128:129]
	v_pk_mul_f32 v[128:129], v[116:117], v[116:117]
	v_pk_mul_f32 v[146:147], v[114:115], v[114:115]
	v_mov_b32_e32 v148, v128
	v_mov_b32_e32 v149, v146
	v_mov_b32_e32 v146, v129
	v_pk_add_f32 v[128:129], v[148:149], v[146:147]
	v_add_f32_e32 v126, v126, v127
	v_add_f32_e32 v126, v126, v129
	v_add_f32_e32 v126, v128, v126
	v_and_b32_e32 v128, 64, v160
	v_add_u32_e32 v128, 64, v128
	v_mov_b32_e32 v127, v126
	s_nop 1
	v_permlane16_swap_b32_e32 v126, v127
	v_add_f32_e32 v126, v126, v127
	v_mov_b32_e32 v127, v126
	s_nop 1
	v_permlane32_swap_b32_e32 v126, v127
	v_add_f32_e32 v126, v126, v127
	v_max_f32_e32 v127, v162, v162
	v_max_f32_e32 v150, v127, v126

.LBB0_213:
	v_cvt_pk_bf16_f32 v114, v126, v127
	v_cvt_pk_bf16_f32 v115, v128, v129
	v_cvt_pk_bf16_f32 v116, v146, v147
	v_cvt_pk_bf16_f32 v117, v148, v149
	s_and_b64 vcc, exec, s[8:9]
	s_mov_b64 s[72:73], -1
	global_store_dwordx4 v[124:125], v[114:117], off offset:256
	s_cbranch_vccnz .LBB0_225
	s_and_b64 vcc, exec, s[6:7]
	s_cbranch_vccnz .LBB0_222
	s_andn2_b64 vcc, exec, s[56:57]
	s_cbranch_vccnz .LBB0_219
	s_andn2_b64 vcc, exec, s[54:55]
	v_mov_b32_e32 v124, v150
	s_cbranch_vccnz .LBB0_218
	v_pk_mul_f32 v[114:115], v[112:113], v[112:113]
	v_pk_mul_f32 v[116:117], v[110:111], v[110:111]
	s_nop 0
	v_pk_mov_b32 v[118:119], v[116:117], v[114:115] op_sel:[1,0]
	v_mov_b32_e32 v117, v115
	v_pk_add_f32 v[114:115], v[118:119], v[116:117]
	v_pk_mul_f32 v[116:117], v[108:109], v[108:109]
	v_pk_mul_f32 v[118:119], v[106:107], v[106:107]
	v_mov_b32_e32 v120, v116
	v_mov_b32_e32 v121, v118
	v_mov_b32_e32 v118, v117
	v_pk_add_f32 v[116:117], v[120:121], v[118:119]
	v_add_f32_e32 v114, v114, v115
	v_add_f32_e32 v114, v114, v117
	v_add_f32_e32 v114, v116, v114
	v_and_b32_e32 v116, 64, v160
	v_add_u32_e32 v116, 64, v116
	v_mov_b32_e32 v115, v114
	s_nop 1
	v_permlane16_swap_b32_e32 v114, v115
	v_add_f32_e32 v114, v114, v115
	v_mov_b32_e32 v115, v114
	s_nop 1
	v_permlane32_swap_b32_e32 v114, v115
	v_add_f32_e32 v114, v114, v115
	v_max_f32_e32 v115, v150, v150
	v_max_f32_e32 v124, v115, v114

.LBB0_227:
	v_or_b32_e32 v106, 16, v161
	v_mad_i64_i32 v[106:107], s[72:73], s70, v106, 0
	v_lshl_add_u64 v[106:107], v[106:107], 1, v[122:123]
	v_cvt_pk_bf16_f32 v108, v114, v115
	v_cvt_pk_bf16_f32 v109, v116, v117
	v_cvt_pk_bf16_f32 v110, v118, v119
	v_cvt_pk_bf16_f32 v111, v120, v121
	s_and_b64 vcc, exec, s[8:9]
	s_mov_b64 s[72:73], -1
	global_store_dwordx4 v[106:107], v[108:111], off
	s_cbranch_vccnz .LBB0_239
	s_and_b64 vcc, exec, s[6:7]
	s_cbranch_vccnz .LBB0_236
	s_andn2_b64 vcc, exec, s[56:57]
	s_cbranch_vccnz .LBB0_233
	s_andn2_b64 vcc, exec, s[54:55]
	v_mov_b32_e32 v116, v124
	s_cbranch_vccnz .LBB0_232
	v_pk_mul_f32 v[108:109], v[104:105], v[104:105]
	v_pk_mul_f32 v[110:111], v[102:103], v[102:103]
	s_nop 0
	v_pk_mov_b32 v[112:113], v[110:111], v[108:109] op_sel:[1,0]
	v_mov_b32_e32 v111, v109
	v_pk_add_f32 v[108:109], v[112:113], v[110:111]
	v_pk_mul_f32 v[110:111], v[100:101], v[100:101]
	v_pk_mul_f32 v[112:113], v[98:99], v[98:99]
	v_mov_b32_e32 v114, v110
	v_mov_b32_e32 v115, v112
	v_mov_b32_e32 v112, v111
	v_pk_add_f32 v[110:111], v[114:115], v[112:113]
	v_add_f32_e32 v108, v108, v109
	v_add_f32_e32 v108, v108, v111
	v_add_f32_e32 v108, v110, v108
	v_and_b32_e32 v110, 64, v160
	v_add_u32_e32 v110, 64, v110
	v_mov_b32_e32 v109, v108
	s_nop 1
	v_permlane16_swap_b32_e32 v108, v109
	v_add_f32_e32 v108, v108, v109
	v_mov_b32_e32 v109, v108
	s_nop 1
	v_permlane32_swap_b32_e32 v108, v109
	v_add_f32_e32 v108, v108, v109
	v_max_f32_e32 v109, v124, v124
	v_max_f32_e32 v116, v109, v108

.LBB0_241:
	v_cvt_pk_bf16_f32 v98, v108, v109
	v_cvt_pk_bf16_f32 v99, v110, v111
	v_cvt_pk_bf16_f32 v100, v112, v113
	v_cvt_pk_bf16_f32 v101, v114, v115
	s_and_b64 vcc, exec, s[8:9]
	s_mov_b64 s[72:73], -1
	global_store_dwordx4 v[106:107], v[98:101], off offset:256
	s_cbranch_vccnz .LBB0_253
	s_and_b64 vcc, exec, s[6:7]
	s_cbranch_vccnz .LBB0_250
	s_andn2_b64 vcc, exec, s[56:57]
	s_cbranch_vccnz .LBB0_247
	s_andn2_b64 vcc, exec, s[54:55]
	v_mov_b32_e32 v106, v116
	s_cbranch_vccnz .LBB0_246
	v_pk_mul_f32 v[98:99], v[96:97], v[96:97]
	v_pk_mul_f32 v[100:101], v[94:95], v[94:95]
	s_nop 0
	v_pk_mov_b32 v[102:103], v[100:101], v[98:99] op_sel:[1,0]
	v_mov_b32_e32 v101, v99
	v_pk_add_f32 v[98:99], v[102:103], v[100:101]
	v_pk_mul_f32 v[100:101], v[92:93], v[92:93]
	v_pk_mul_f32 v[102:103], v[90:91], v[90:91]
	v_mov_b32_e32 v104, v100
	v_mov_b32_e32 v105, v102
	v_mov_b32_e32 v102, v101
	v_pk_add_f32 v[100:101], v[104:105], v[102:103]
	v_add_f32_e32 v98, v98, v99
	v_add_f32_e32 v98, v98, v101
	v_add_f32_e32 v98, v100, v98
	v_and_b32_e32 v100, 64, v160
	v_add_u32_e32 v100, 64, v100
	v_mov_b32_e32 v99, v98
	s_nop 1
	v_permlane16_swap_b32_e32 v98, v99
	v_add_f32_e32 v98, v98, v99
	v_mov_b32_e32 v99, v98
	s_nop 1
	v_permlane32_swap_b32_e32 v98, v99
	v_add_f32_e32 v98, v98, v99
	v_max_f32_e32 v99, v116, v116
	v_max_f32_e32 v106, v99, v98

.LBB0_255:
	v_or_b32_e32 v90, 32, v161
	v_mad_i64_i32 v[90:91], s[72:73], s70, v90, 0
	v_lshl_add_u64 v[90:91], v[90:91], 1, v[122:123]
	v_cvt_pk_bf16_f32 v92, v98, v99
	v_cvt_pk_bf16_f32 v93, v100, v101
	v_cvt_pk_bf16_f32 v94, v102, v103
	v_cvt_pk_bf16_f32 v95, v104, v105
	s_and_b64 vcc, exec, s[8:9]
	s_mov_b64 s[72:73], -1
	global_store_dwordx4 v[90:91], v[92:95], off
	s_cbranch_vccnz .LBB0_267
	s_and_b64 vcc, exec, s[6:7]
	s_cbranch_vccnz .LBB0_264
	s_andn2_b64 vcc, exec, s[56:57]
	s_cbranch_vccnz .LBB0_261
	s_andn2_b64 vcc, exec, s[54:55]
	v_mov_b32_e32 v100, v106
	s_cbranch_vccnz .LBB0_260
	v_pk_mul_f32 v[92:93], v[88:89], v[88:89]
	v_pk_mul_f32 v[94:95], v[86:87], v[86:87]
	s_nop 0
	v_pk_mov_b32 v[96:97], v[94:95], v[92:93] op_sel:[1,0]
	v_mov_b32_e32 v95, v93
	v_pk_add_f32 v[92:93], v[96:97], v[94:95]
	v_pk_mul_f32 v[94:95], v[84:85], v[84:85]
	v_pk_mul_f32 v[96:97], v[82:83], v[82:83]
	v_mov_b32_e32 v98, v94
	v_mov_b32_e32 v99, v96
	v_mov_b32_e32 v96, v95
	v_pk_add_f32 v[94:95], v[98:99], v[96:97]
	v_add_f32_e32 v92, v92, v93
	v_add_f32_e32 v92, v92, v95
	v_add_f32_e32 v92, v94, v92
	v_and_b32_e32 v94, 64, v160
	v_add_u32_e32 v94, 64, v94
	v_mov_b32_e32 v93, v92
	s_nop 1
	v_permlane16_swap_b32_e32 v92, v93
	v_add_f32_e32 v92, v92, v93
	v_mov_b32_e32 v93, v92
	s_nop 1
	v_permlane32_swap_b32_e32 v92, v93
	v_add_f32_e32 v92, v92, v93
	v_max_f32_e32 v93, v106, v106
	v_max_f32_e32 v100, v93, v92

.LBB0_269:
	v_cvt_pk_bf16_f32 v82, v92, v93
	v_cvt_pk_bf16_f32 v83, v94, v95
	v_cvt_pk_bf16_f32 v84, v96, v97
	v_cvt_pk_bf16_f32 v85, v98, v99
	s_and_b64 vcc, exec, s[8:9]
	s_mov_b64 s[72:73], -1
	global_store_dwordx4 v[90:91], v[82:85], off offset:256
	s_cbranch_vccnz .LBB0_281
	s_and_b64 vcc, exec, s[6:7]
	s_cbranch_vccnz .LBB0_278
	s_andn2_b64 vcc, exec, s[56:57]
	s_cbranch_vccnz .LBB0_275
	s_andn2_b64 vcc, exec, s[54:55]
	v_mov_b32_e32 v90, v100
	s_cbranch_vccnz .LBB0_274
	v_pk_mul_f32 v[82:83], v[80:81], v[80:81]
	v_pk_mul_f32 v[84:85], v[78:79], v[78:79]
	s_nop 0
	v_pk_mov_b32 v[86:87], v[84:85], v[82:83] op_sel:[1,0]
	v_mov_b32_e32 v85, v83
	v_pk_add_f32 v[82:83], v[86:87], v[84:85]
	v_pk_mul_f32 v[84:85], v[76:77], v[76:77]
	v_pk_mul_f32 v[86:87], v[74:75], v[74:75]
	v_mov_b32_e32 v88, v84
	v_mov_b32_e32 v89, v86
	v_mov_b32_e32 v86, v85
	v_pk_add_f32 v[84:85], v[88:89], v[86:87]
	v_add_f32_e32 v82, v82, v83
	v_add_f32_e32 v82, v82, v85
	v_add_f32_e32 v82, v84, v82
	v_and_b32_e32 v84, 64, v160
	v_add_u32_e32 v84, 64, v84
	v_mov_b32_e32 v83, v82
	s_nop 1
	v_permlane16_swap_b32_e32 v82, v83
	v_add_f32_e32 v82, v82, v83
	v_mov_b32_e32 v83, v82
	s_nop 1
	v_permlane32_swap_b32_e32 v82, v83
	v_add_f32_e32 v82, v82, v83
	v_max_f32_e32 v83, v100, v100
	v_max_f32_e32 v90, v83, v82

.LBB0_283:
	v_or_b32_e32 v74, 48, v161
	v_mad_i64_i32 v[74:75], s[72:73], s70, v74, 0
	v_lshl_add_u64 v[74:75], v[74:75], 1, v[122:123]
	v_cvt_pk_bf16_f32 v76, v82, v83
	v_cvt_pk_bf16_f32 v77, v84, v85
	v_cvt_pk_bf16_f32 v78, v86, v87
	v_cvt_pk_bf16_f32 v79, v88, v89
	s_and_b64 vcc, exec, s[8:9]
	s_mov_b64 s[72:73], -1
	global_store_dwordx4 v[74:75], v[76:79], off
	s_cbranch_vccnz .LBB0_295
	s_and_b64 vcc, exec, s[6:7]
	s_cbranch_vccnz .LBB0_292
	s_andn2_b64 vcc, exec, s[56:57]
	s_cbranch_vccnz .LBB0_289
	s_andn2_b64 vcc, exec, s[54:55]
	v_mov_b32_e32 v84, v90
	s_cbranch_vccnz .LBB0_288
	v_pk_mul_f32 v[76:77], v[72:73], v[72:73]
	v_pk_mul_f32 v[78:79], v[70:71], v[70:71]
	s_nop 0
	v_pk_mov_b32 v[80:81], v[78:79], v[76:77] op_sel:[1,0]
	v_mov_b32_e32 v79, v77
	v_pk_add_f32 v[76:77], v[80:81], v[78:79]
	v_pk_mul_f32 v[78:79], v[68:69], v[68:69]
	v_pk_mul_f32 v[80:81], v[66:67], v[66:67]
	v_mov_b32_e32 v82, v78
	v_mov_b32_e32 v83, v80
	v_mov_b32_e32 v80, v79
	v_pk_add_f32 v[78:79], v[82:83], v[80:81]
	v_add_f32_e32 v76, v76, v77
	v_add_f32_e32 v76, v76, v79
	v_add_f32_e32 v76, v78, v76
	v_and_b32_e32 v78, 64, v160
	v_add_u32_e32 v78, 64, v78
	v_mov_b32_e32 v77, v76
	s_nop 1
	v_permlane16_swap_b32_e32 v76, v77
	v_add_f32_e32 v76, v76, v77
	v_mov_b32_e32 v77, v76
	s_nop 1
	v_permlane32_swap_b32_e32 v76, v77
	v_add_f32_e32 v76, v76, v77
	v_max_f32_e32 v77, v90, v90
	v_max_f32_e32 v84, v77, v76

.LBB0_297:
	v_cvt_pk_bf16_f32 v66, v76, v77
	v_cvt_pk_bf16_f32 v67, v78, v79
	v_cvt_pk_bf16_f32 v68, v80, v81
	v_cvt_pk_bf16_f32 v69, v82, v83
	s_and_b64 vcc, exec, s[8:9]
	s_mov_b64 s[72:73], -1
	global_store_dwordx4 v[74:75], v[66:69], off offset:256
	s_cbranch_vccnz .LBB0_309
	s_and_b64 vcc, exec, s[6:7]
	s_cbranch_vccnz .LBB0_306
	s_andn2_b64 vcc, exec, s[56:57]
	s_cbranch_vccnz .LBB0_303
	s_andn2_b64 vcc, exec, s[54:55]
	v_mov_b32_e32 v74, v84
	s_cbranch_vccnz .LBB0_302
	v_pk_mul_f32 v[66:67], v[64:65], v[64:65]
	v_pk_mul_f32 v[68:69], v[62:63], v[62:63]
	s_nop 0
	v_pk_mov_b32 v[70:71], v[68:69], v[66:67] op_sel:[1,0]
	v_mov_b32_e32 v69, v67
	v_pk_add_f32 v[66:67], v[70:71], v[68:69]
	v_pk_mul_f32 v[68:69], v[60:61], v[60:61]
	v_pk_mul_f32 v[70:71], v[58:59], v[58:59]
	v_mov_b32_e32 v72, v68
	v_mov_b32_e32 v73, v70
	v_mov_b32_e32 v70, v69
	v_pk_add_f32 v[68:69], v[72:73], v[70:71]
	v_add_f32_e32 v66, v66, v67
	v_add_f32_e32 v66, v66, v69
	v_add_f32_e32 v66, v68, v66
	v_and_b32_e32 v68, 64, v160
	v_add_u32_e32 v68, 64, v68
	v_mov_b32_e32 v67, v66
	s_nop 1
	v_permlane16_swap_b32_e32 v66, v67
	v_add_f32_e32 v66, v66, v67
	v_mov_b32_e32 v67, v66
	s_nop 1
	v_permlane32_swap_b32_e32 v66, v67
	v_add_f32_e32 v66, v66, v67
	v_max_f32_e32 v67, v84, v84
	v_max_f32_e32 v74, v67, v66

.LBB0_311:
	v_add_u32_e32 v58, 0x80, v161
	v_mad_i64_i32 v[58:59], s[72:73], s70, v58, 0
	v_lshl_add_u64 v[58:59], v[58:59], 1, v[122:123]
	v_cvt_pk_bf16_f32 v60, v66, v67
	v_cvt_pk_bf16_f32 v61, v68, v69
	v_cvt_pk_bf16_f32 v62, v70, v71
	v_cvt_pk_bf16_f32 v63, v72, v73
	s_and_b64 vcc, exec, s[8:9]
	s_mov_b64 s[72:73], -1
	global_store_dwordx4 v[58:59], v[60:63], off
	s_cbranch_vccnz .LBB0_323
	s_and_b64 vcc, exec, s[6:7]
	s_cbranch_vccnz .LBB0_320
	s_andn2_b64 vcc, exec, s[56:57]
	s_cbranch_vccnz .LBB0_317
	s_andn2_b64 vcc, exec, s[54:55]
	v_mov_b32_e32 v68, v74
	s_cbranch_vccnz .LBB0_316
	v_pk_mul_f32 v[60:61], v[56:57], v[56:57]
	v_pk_mul_f32 v[62:63], v[54:55], v[54:55]
	s_nop 0
	v_pk_mov_b32 v[64:65], v[62:63], v[60:61] op_sel:[1,0]
	v_mov_b32_e32 v63, v61
	v_pk_add_f32 v[60:61], v[64:65], v[62:63]
	v_pk_mul_f32 v[62:63], v[52:53], v[52:53]
	v_pk_mul_f32 v[64:65], v[50:51], v[50:51]
	v_mov_b32_e32 v66, v62
	v_mov_b32_e32 v67, v64
	v_mov_b32_e32 v64, v63
	v_pk_add_f32 v[62:63], v[66:67], v[64:65]
	v_add_f32_e32 v60, v60, v61
	v_add_f32_e32 v60, v60, v63
	v_add_f32_e32 v60, v62, v60
	v_and_b32_e32 v62, 64, v160
	v_add_u32_e32 v62, 64, v62
	v_mov_b32_e32 v61, v60
	s_nop 1
	v_permlane16_swap_b32_e32 v60, v61
	v_add_f32_e32 v60, v60, v61
	v_mov_b32_e32 v61, v60
	s_nop 1
	v_permlane32_swap_b32_e32 v60, v61
	v_add_f32_e32 v60, v60, v61
	v_max_f32_e32 v61, v74, v74
	v_max_f32_e32 v68, v61, v60

.LBB0_325:
	v_cvt_pk_bf16_f32 v50, v60, v61
	v_cvt_pk_bf16_f32 v51, v62, v63
	v_cvt_pk_bf16_f32 v52, v64, v65
	v_cvt_pk_bf16_f32 v53, v66, v67
	s_and_b64 vcc, exec, s[8:9]
	s_mov_b64 s[72:73], -1
	global_store_dwordx4 v[58:59], v[50:53], off offset:256
	s_cbranch_vccnz .LBB0_337
	s_and_b64 vcc, exec, s[6:7]
	s_cbranch_vccnz .LBB0_334
	s_andn2_b64 vcc, exec, s[56:57]
	s_cbranch_vccnz .LBB0_331
	s_andn2_b64 vcc, exec, s[54:55]
	v_mov_b32_e32 v58, v68
	s_cbranch_vccnz .LBB0_330
	v_pk_mul_f32 v[50:51], v[48:49], v[48:49]
	v_pk_mul_f32 v[52:53], v[46:47], v[46:47]
	s_nop 0
	v_pk_mov_b32 v[54:55], v[52:53], v[50:51] op_sel:[1,0]
	v_mov_b32_e32 v53, v51
	v_pk_add_f32 v[50:51], v[54:55], v[52:53]
	v_pk_mul_f32 v[52:53], v[44:45], v[44:45]
	v_pk_mul_f32 v[54:55], v[42:43], v[42:43]
	v_mov_b32_e32 v56, v52
	v_mov_b32_e32 v57, v54
	v_mov_b32_e32 v54, v53
	v_pk_add_f32 v[52:53], v[56:57], v[54:55]
	v_add_f32_e32 v50, v50, v51
	v_add_f32_e32 v50, v50, v53
	v_add_f32_e32 v50, v52, v50
	v_and_b32_e32 v52, 64, v160
	v_add_u32_e32 v52, 64, v52
	v_mov_b32_e32 v51, v50
	s_nop 1
	v_permlane16_swap_b32_e32 v50, v51
	v_add_f32_e32 v50, v50, v51
	v_mov_b32_e32 v51, v50
	s_nop 1
	v_permlane32_swap_b32_e32 v50, v51
	v_add_f32_e32 v50, v50, v51
	v_max_f32_e32 v51, v68, v68
	v_max_f32_e32 v58, v51, v50

.LBB0_339:
	v_add_u32_e32 v42, 0x90, v161
	v_mad_i64_i32 v[42:43], s[72:73], s70, v42, 0
	v_lshl_add_u64 v[42:43], v[42:43], 1, v[122:123]
	v_cvt_pk_bf16_f32 v44, v50, v51
	v_cvt_pk_bf16_f32 v45, v52, v53
	v_cvt_pk_bf16_f32 v46, v54, v55
	v_cvt_pk_bf16_f32 v47, v56, v57
	s_and_b64 vcc, exec, s[8:9]
	s_mov_b64 s[72:73], -1
	global_store_dwordx4 v[42:43], v[44:47], off
	s_cbranch_vccnz .LBB0_351
	s_and_b64 vcc, exec, s[6:7]
	s_cbranch_vccnz .LBB0_348
	s_andn2_b64 vcc, exec, s[56:57]
	s_cbranch_vccnz .LBB0_345
	s_andn2_b64 vcc, exec, s[54:55]
	v_mov_b32_e32 v52, v58
	s_cbranch_vccnz .LBB0_344
	v_pk_mul_f32 v[44:45], v[40:41], v[40:41]
	v_pk_mul_f32 v[46:47], v[38:39], v[38:39]
	s_nop 0
	v_pk_mov_b32 v[48:49], v[46:47], v[44:45] op_sel:[1,0]
	v_mov_b32_e32 v47, v45
	v_pk_add_f32 v[44:45], v[48:49], v[46:47]
	v_pk_mul_f32 v[46:47], v[36:37], v[36:37]
	v_pk_mul_f32 v[48:49], v[34:35], v[34:35]
	v_mov_b32_e32 v50, v46
	v_mov_b32_e32 v51, v48
	v_mov_b32_e32 v48, v47
	v_pk_add_f32 v[46:47], v[50:51], v[48:49]
	v_add_f32_e32 v44, v44, v45
	v_add_f32_e32 v44, v44, v47
	v_add_f32_e32 v44, v46, v44
	v_and_b32_e32 v46, 64, v160
	v_add_u32_e32 v46, 64, v46
	v_mov_b32_e32 v45, v44
	s_nop 1
	v_permlane16_swap_b32_e32 v44, v45
	v_add_f32_e32 v44, v44, v45
	v_mov_b32_e32 v45, v44
	s_nop 1
	v_permlane32_swap_b32_e32 v44, v45
	v_add_f32_e32 v44, v44, v45
	v_max_f32_e32 v45, v58, v58
	v_max_f32_e32 v52, v45, v44

.LBB0_353:
	v_cvt_pk_bf16_f32 v34, v44, v45
	v_cvt_pk_bf16_f32 v35, v46, v47
	v_cvt_pk_bf16_f32 v36, v48, v49
	v_cvt_pk_bf16_f32 v37, v50, v51
	s_and_b64 vcc, exec, s[8:9]
	s_mov_b64 s[72:73], -1
	global_store_dwordx4 v[42:43], v[34:37], off offset:256
	s_cbranch_vccnz .LBB0_365
	s_and_b64 vcc, exec, s[6:7]
	s_cbranch_vccnz .LBB0_362
	s_andn2_b64 vcc, exec, s[56:57]
	s_cbranch_vccnz .LBB0_359
	s_andn2_b64 vcc, exec, s[54:55]
	v_mov_b32_e32 v42, v52
	s_cbranch_vccnz .LBB0_358
	v_pk_mul_f32 v[34:35], v[32:33], v[32:33]
	v_pk_mul_f32 v[36:37], v[30:31], v[30:31]
	s_nop 0
	v_pk_mov_b32 v[38:39], v[36:37], v[34:35] op_sel:[1,0]
	v_mov_b32_e32 v37, v35
	v_pk_add_f32 v[34:35], v[38:39], v[36:37]
	v_pk_mul_f32 v[36:37], v[28:29], v[28:29]
	v_pk_mul_f32 v[38:39], v[26:27], v[26:27]
	v_mov_b32_e32 v40, v36
	v_mov_b32_e32 v41, v38
	v_mov_b32_e32 v38, v37
	v_pk_add_f32 v[36:37], v[40:41], v[38:39]
	v_add_f32_e32 v34, v34, v35
	v_add_f32_e32 v34, v34, v37
	v_add_f32_e32 v34, v36, v34
	v_and_b32_e32 v36, 64, v160
	v_add_u32_e32 v36, 64, v36
	v_mov_b32_e32 v35, v34
	s_nop 1
	v_permlane16_swap_b32_e32 v34, v35
	v_add_f32_e32 v34, v34, v35
	v_mov_b32_e32 v35, v34
	s_nop 1
	v_permlane32_swap_b32_e32 v34, v35
	v_add_f32_e32 v34, v34, v35
	v_max_f32_e32 v35, v52, v52
	v_max_f32_e32 v42, v35, v34

.LBB0_367:
	v_add_u32_e32 v26, 0xa0, v161
	v_mad_i64_i32 v[26:27], s[72:73], s70, v26, 0
	v_lshl_add_u64 v[26:27], v[26:27], 1, v[122:123]
	v_cvt_pk_bf16_f32 v28, v34, v35
	v_cvt_pk_bf16_f32 v29, v36, v37
	v_cvt_pk_bf16_f32 v30, v38, v39
	v_cvt_pk_bf16_f32 v31, v40, v41
	s_and_b64 vcc, exec, s[8:9]
	s_mov_b64 s[72:73], -1
	global_store_dwordx4 v[26:27], v[28:31], off
	s_cbranch_vccnz .LBB0_379
	s_and_b64 vcc, exec, s[6:7]
	s_cbranch_vccnz .LBB0_376
	s_andn2_b64 vcc, exec, s[56:57]
	s_cbranch_vccnz .LBB0_373
	s_andn2_b64 vcc, exec, s[54:55]
	v_mov_b32_e32 v36, v42
	s_cbranch_vccnz .LBB0_372
	v_pk_mul_f32 v[28:29], v[24:25], v[24:25]
	v_pk_mul_f32 v[30:31], v[22:23], v[22:23]
	s_nop 0
	v_pk_mov_b32 v[32:33], v[30:31], v[28:29] op_sel:[1,0]
	v_mov_b32_e32 v31, v29
	v_pk_add_f32 v[28:29], v[32:33], v[30:31]
	v_pk_mul_f32 v[30:31], v[20:21], v[20:21]
	v_pk_mul_f32 v[32:33], v[18:19], v[18:19]
	v_mov_b32_e32 v34, v30
	v_mov_b32_e32 v35, v32
	v_mov_b32_e32 v32, v31
	v_pk_add_f32 v[30:31], v[34:35], v[32:33]
	v_add_f32_e32 v28, v28, v29
	v_add_f32_e32 v28, v28, v31
	v_add_f32_e32 v28, v30, v28
	v_and_b32_e32 v30, 64, v160
	v_add_u32_e32 v30, 64, v30
	v_mov_b32_e32 v29, v28
	s_nop 1
	v_permlane16_swap_b32_e32 v28, v29
	v_add_f32_e32 v28, v28, v29
	v_mov_b32_e32 v29, v28
	s_nop 1
	v_permlane32_swap_b32_e32 v28, v29
	v_add_f32_e32 v28, v28, v29
	v_max_f32_e32 v29, v42, v42
	v_max_f32_e32 v36, v29, v28

.LBB0_381:
	v_cvt_pk_bf16_f32 v18, v28, v29
	v_cvt_pk_bf16_f32 v19, v30, v31
	v_cvt_pk_bf16_f32 v20, v32, v33
	v_cvt_pk_bf16_f32 v21, v34, v35
	s_and_b64 vcc, exec, s[8:9]
	s_mov_b64 s[72:73], -1
	global_store_dwordx4 v[26:27], v[18:21], off offset:256
	s_cbranch_vccnz .LBB0_393
	s_and_b64 vcc, exec, s[6:7]
	s_cbranch_vccnz .LBB0_390
	s_andn2_b64 vcc, exec, s[56:57]
	s_cbranch_vccnz .LBB0_387
	s_andn2_b64 vcc, exec, s[54:55]
	v_mov_b32_e32 v26, v36
	s_cbranch_vccnz .LBB0_386
	v_pk_mul_f32 v[18:19], v[16:17], v[16:17]
	v_pk_mul_f32 v[20:21], v[14:15], v[14:15]
	s_nop 0
	v_pk_mov_b32 v[22:23], v[20:21], v[18:19] op_sel:[1,0]
	v_mov_b32_e32 v21, v19
	v_pk_add_f32 v[18:19], v[22:23], v[20:21]
	v_pk_mul_f32 v[20:21], v[12:13], v[12:13]
	v_pk_mul_f32 v[22:23], v[10:11], v[10:11]
	v_mov_b32_e32 v24, v20
	v_mov_b32_e32 v25, v22
	v_mov_b32_e32 v22, v21
	v_pk_add_f32 v[20:21], v[24:25], v[22:23]
	v_add_f32_e32 v18, v18, v19
	v_add_f32_e32 v18, v18, v21
	v_add_f32_e32 v18, v20, v18
	v_and_b32_e32 v20, 64, v160
	v_add_u32_e32 v20, 64, v20
	v_mov_b32_e32 v19, v18
	s_nop 1
	v_permlane16_swap_b32_e32 v18, v19
	v_add_f32_e32 v18, v18, v19
	v_mov_b32_e32 v19, v18
	s_nop 1
	v_permlane32_swap_b32_e32 v18, v19
	v_add_f32_e32 v18, v18, v19
	v_max_f32_e32 v19, v36, v36
	v_max_f32_e32 v26, v19, v18

.LBB0_395:
	v_add_u32_e32 v10, 0xb0, v161
	v_mad_i64_i32 v[10:11], s[70:71], s70, v10, 0
	v_lshl_add_u64 v[10:11], v[10:11], 1, v[122:123]
	v_cvt_pk_bf16_f32 v12, v18, v19
	v_cvt_pk_bf16_f32 v13, v20, v21
	v_cvt_pk_bf16_f32 v14, v22, v23
	v_cvt_pk_bf16_f32 v15, v24, v25
	s_and_b64 vcc, exec, s[8:9]
	s_mov_b64 s[8:9], -1
	global_store_dwordx4 v[10:11], v[12:15], off
	s_cbranch_vccnz .LBB0_407
	s_and_b64 vcc, exec, s[6:7]
	s_mov_b64 s[6:7], -1
	s_cbranch_vccnz .LBB0_404
	s_andn2_b64 vcc, exec, s[56:57]
	s_cbranch_vccnz .LBB0_401
	s_andn2_b64 vcc, exec, s[54:55]
	v_mov_b32_e32 v20, v26
	s_cbranch_vccnz .LBB0_400
	v_pk_mul_f32 v[12:13], v[8:9], v[8:9]
	v_pk_mul_f32 v[14:15], v[6:7], v[6:7]
	s_nop 0
	v_pk_mov_b32 v[16:17], v[14:15], v[12:13] op_sel:[1,0]
	v_mov_b32_e32 v15, v13
	v_pk_add_f32 v[12:13], v[16:17], v[14:15]
	v_pk_mul_f32 v[14:15], v[4:5], v[4:5]
	v_pk_mul_f32 v[16:17], v[2:3], v[2:3]
	v_mov_b32_e32 v18, v14
	v_mov_b32_e32 v19, v16
	v_mov_b32_e32 v16, v15
	v_pk_add_f32 v[14:15], v[18:19], v[16:17]
	v_add_f32_e32 v12, v12, v13
	v_add_f32_e32 v12, v12, v15
	v_add_f32_e32 v12, v14, v12
	v_and_b32_e32 v14, 64, v160
	v_add_u32_e32 v14, 64, v14
	v_mov_b32_e32 v13, v12
	s_nop 1
	v_permlane16_swap_b32_e32 v12, v13
	v_add_f32_e32 v12, v12, v13
	v_mov_b32_e32 v13, v12
	s_nop 1
	v_permlane32_swap_b32_e32 v12, v13
	v_add_f32_e32 v12, v12, v13
	v_max_f32_e32 v13, v26, v26
	v_max_f32_e32 v20, v13, v12
